# prologue de-serialisation for prep_task<8>: the two raw-row staging loads are issued together (one wait) instead of two load-wait-write rounds
# baseline (speedup 1.0000x reference)
.LBB0_752:
	v_ashrrev_i32_e32 v120, 6, v6
	s_movk_i32 s2, 0x80
	v_add3_u32 v121, v120, s7, 0
	v_cmp_gt_u32_e32 vcc, s52, v121
	v_mov_b32_e32 v126, 0
	s_and_saveexec_b64 s[48:49], vcc
	v_add_u32_e32 v7, s6, v121
	v_mov_b64_e32 v[8:9], s[44:45]
	v_mad_i64_i32 v[8:9], s[50:51], v7, s8, v[8:9]
	v_lshl_add_u64 v[8:9], v[8:9], 0, v[0:1]
	v_add_co_u32_e32 v8, vcc, 0x1000, v8
	s_nop 1
	v_addc_co_u32_e32 v9, vcc, 0, v9, vcc
	global_load_ushort v126, v[8:9], off offset:2592
	s_or_b64 exec, exec, s[48:49]
	v_add3_u32 v122, v120, s7, 8
	v_cmp_gt_u32_e32 vcc, s52, v122
	v_cmp_gt_i32_e64 s[46:47], s2, v6
	v_mov_b32_e32 v127, 0
	s_and_b64 vcc, vcc, s[46:47]
	s_and_saveexec_b64 s[48:49], vcc
	v_add_u32_e32 v7, s6, v122
	v_mov_b64_e32 v[8:9], s[44:45]
	v_mad_i64_i32 v[8:9], s[50:51], v7, s8, v[8:9]
	v_lshl_add_u64 v[8:9], v[8:9], 0, v[0:1]
	v_add_co_u32_e32 v8, vcc, 0x1000, v8
	s_nop 1
	v_addc_co_u32_e32 v9, vcc, 0, v9, vcc
	global_load_ushort v127, v[8:9], off offset:2592
	s_or_b64 exec, exec, s[48:49]
	s_waitcnt vmcnt(1)
	v_lshlrev_b32_e32 v126, 16, v126
	ds_write_b32 v5, v126
	s_waitcnt vmcnt(0)
	v_lshlrev_b32_e32 v127, 16, v127
	v_cmp_gt_i32_e32 vcc, s2, v6
	s_and_saveexec_b64 s[48:49], vcc
	ds_write_b32 v5, v127 offset:2048
	s_or_b64 exec, exec, s[48:49]
